# grid barrier: flat release (all workgroups poll the top arrival counter) and the L1 invalidate issued at barrier entry so it overlaps the arrival round trip
# speedup vs baseline: 1.0151x; 1.0108x over previous
; __device__ __forceinline__ void xcd_barrier(const XcdBarrier& b) {
;     asm volatile("s_waitcnt vmcnt(0)" ::: "memory");
;     __syncthreads();
;     if (threadIdx.x == 0) {
;         unsigned* bar = b.bar;
;         __builtin_amdgcn_s_waitcnt(0);
;         unsigned nloc = b.st[0], nx = b.st[1];
;         if (nloc == 0u) { xcd_barrier_complete(bar, b.x, nloc, nx); b.st[0] = nloc; b.st[1] = nx; }
.LBB0_262:
	s_or_b64 exec, exec, s[6:7]
	s_cmp_lt_i32 s53, 3
	s_cbranch_scc1 .LBB0_330
	s_cmpk_lt_u32 s53, 0x3e9
	s_waitcnt lgkmcnt(0)
	s_mov_b64 s[4:5], -1
	s_cbranch_scc0 .LBB0_317
	s_waitcnt vmcnt(0)
	s_barrier
	s_and_saveexec_b64 s[4:5], s[86:87]
	s_cbranch_execz .LBB0_316
	buffer_inv sc1
	v_mov_b32_e32 v2, 0x27ff0
	s_waitcnt lgkmcnt(0)
	ds_read_b32 v4, v2
	v_mov_b32_e32 v2, 0x27ff4
	ds_read_b32 v2, v2
	s_waitcnt lgkmcnt(1)
	v_cmp_ne_u32_e32 vcc, 0, v4
	s_cbranch_vccnz .LBB0_280
	s_add_u32 s6, s66, 0x1000
	s_addc_u32 s7, s67, 0
	s_add_u32 s8, s66, 0x1100
	s_addc_u32 s9, s67, 0
	s_add_u32 s10, s66, 0x1200
	s_addc_u32 s11, s67, 0
	s_mul_i32 s3, s55, s84
	s_add_u32 s12, s66, 0x1300
	s_mul_i32 s3, s3, s54
	s_addc_u32 s13, s67, 0
	s_mov_b32 s20, 1
	v_mov_b32_e32 v18, 0
	s_branch .LBB0_268

; __device__ __forceinline__ unsigned xb_ld(unsigned* p)              { return __hip_atomic_load(p, __ATOMIC_RELAXED, __HIP_MEMORY_SCOPE_AGENT); }
; __device__ __forceinline__ unsigned xb_add(unsigned* p, unsigned v) { return __hip_atomic_fetch_add(p, v, __ATOMIC_RELAXED, __HIP_MEMORY_SCOPE_AGENT); }
; #define XB_SPIN(cond, bar) do { unsigned _sp = 0; while (cond) { __builtin_amdgcn_s_sleep(1); \
;     if ((++_sp & 255u) == 0u) { if (xb_ld(&(bar)[XB_TMO])) break; if (_sp > XB_SPIN_CAP) { atomicAdd(&(bar)[XB_TMO], 1u); break; } } } } while (0)
; __device__ __forceinline__ void xcd_barrier(const XcdBarrier& b) {
;     ...
;         const unsigned old = xb_add(&bar[XB_XSUB(b.x)], 1u);
;         const unsigned gen = old / nloc;
;         if (old + 1u == (gen + 1u) * nloc) {
;             __builtin_amdgcn_fence(__ATOMIC_RELEASE, "agent");
;             asm volatile("s_waitcnt vmcnt(0)" ::: "memory");
;             const unsigned og = xb_add(&bar[XB_TOP], 1u);
;             const unsigned tg = og / nx;
;             if (og + 1u == (tg + 1u) * nx) xb_add(&bar[XB_TOPGEN], 1u);
;             else XB_SPIN(xb_ld(&bar[XB_TOPGEN]) == tg, bar);
;             __builtin_amdgcn_fence(__ATOMIC_ACQUIRE, "agent");
;             xb_add(&bar[XB_XGEN(b.x)], 1u);
;             asm volatile("s_waitcnt vmcnt(0)" ::: "memory");
;         } else {
;             XB_SPIN(xb_ld(&bar[XB_XGEN(b.x)]) == gen, bar);
;             __builtin_amdgcn_fence(__ATOMIC_ACQUIRE, "agent");
;             asm volatile("s_waitcnt vmcnt(0)" ::: "memory");
;         }
.LBB0_282:
	s_or_b64 exec, exec, s[10:11]
	v_cvt_f32_u32_e32 v6, v4
	s_waitcnt vmcnt(0)
	v_readfirstlane_b32 s3, v5
	v_sub_u32_e32 v5, 0, v4
	v_rcp_iflag_f32_e32 v6, v6
	v_add_u32_e32 v7, s3, v3
	v_mul_f32_e32 v6, 0x4f7ffffe, v6
	v_cvt_u32_f32_e32 v6, v6
	v_mul_lo_u32 v3, v5, v6
	v_mul_hi_u32 v3, v6, v3
	v_add_u32_e32 v3, v6, v3
	v_mul_hi_u32 v3, v7, v3
	v_mul_lo_u32 v5, v3, v4
	v_sub_u32_e32 v5, v7, v5
	v_add_u32_e32 v6, 1, v3
	v_cmp_ge_u32_e32 vcc, v5, v4
	s_nop 1
	v_cndmask_b32_e32 v3, v3, v6, vcc
	v_sub_u32_e32 v6, v5, v4
	v_cndmask_b32_e32 v5, v5, v6, vcc
	v_add_u32_e32 v6, 1, v3
	v_cmp_ge_u32_e32 vcc, v5, v4
	v_add_u32_e32 v5, 1, v7
	s_nop 0
	v_cndmask_b32_e32 v3, v3, v6, vcc
	v_mul_lo_u32 v6, v4, v3
	v_add_u32_e32 v4, v6, v4
	v_cmp_ne_u32_e32 vcc, v5, v4
	s_waitcnt lgkmcnt(0)
	v_add_u32_e32 v3, 1, v3
	v_mul_lo_u32 v3, v3, v2
	s_cbranch_vccnz .Lgb1_poll
	buffer_wbl2 sc1
	s_waitcnt vmcnt(0)
	v_mov_b32_e32 v4, 0x3000
	v_mov_b32_e32 v5, 1
	global_atomic_add v4, v5, s[66:67] offset:1024
.Lgb1_poll:
	v_mov_b32_e32 v4, 0x3000
	s_mov_b32 s3, 0
.Lgb1_loop:
	global_load_dword v5, v4, s[66:67] offset:1024 sc1
	s_add_u32 s3, s3, 1
	s_waitcnt vmcnt(0)
	v_cmp_ge_u32_e32 vcc, v5, v3
	s_cbranch_vccnz .Lgb1_done
	s_cmp_lt_u32 s3, 0x40000
	s_cbranch_scc0 .Lgb1_done
	s_sleep 1
	s_branch .Lgb1_loop
.Lgb1_done:
	s_waitcnt vmcnt(0)
.LBB0_316:
	s_or_b64 exec, exec, s[4:5]
	s_mov_b64 s[4:5], 0
	s_waitcnt lgkmcnt(0)
	s_barrier

; __device__ __forceinline__ void xcd_barrier(const XcdBarrier& b) {
;     asm volatile("s_waitcnt vmcnt(0)" ::: "memory");
;     __syncthreads();
;     if (threadIdx.x == 0) {
;         unsigned* bar = b.bar;
;         __builtin_amdgcn_s_waitcnt(0);
;         unsigned nloc = b.st[0], nx = b.st[1];
;         if (nloc == 0u) { xcd_barrier_complete(bar, b.x, nloc, nx); b.st[0] = nloc; b.st[1] = nx; }
.LBB0_1673:
	s_cmp_lt_i32 s53, 4
	s_cbranch_scc1 .LBB0_1741
	s_cmpk_lt_u32 s53, 0x3e9
	s_mov_b64 s[4:5], -1
	s_cbranch_scc0 .LBB0_1728
	s_waitcnt vmcnt(0)
	s_waitcnt lgkmcnt(0)
	s_barrier
	s_and_saveexec_b64 s[4:5], s[86:87]
	s_cbranch_execz .LBB0_1727
	buffer_inv sc1
	v_mov_b32_e32 v2, 0x27ff0
	s_waitcnt lgkmcnt(0)
	ds_read_b32 v4, v2
	v_mov_b32_e32 v2, 0x27ff4
	ds_read_b32 v2, v2
	s_waitcnt lgkmcnt(1)
	v_cmp_ne_u32_e32 vcc, 0, v4
	s_cbranch_vccnz .LBB0_1691
	s_add_u32 s6, s66, 0x1000
	s_addc_u32 s7, s67, 0
	s_add_u32 s8, s66, 0x1100
	s_addc_u32 s9, s67, 0
	s_add_u32 s10, s66, 0x1200
	s_addc_u32 s11, s67, 0
	s_mul_i32 s3, s55, s84
	s_add_u32 s12, s66, 0x1300
	s_mul_i32 s3, s3, s54
	s_addc_u32 s13, s67, 0
	s_mov_b32 s20, 1
	v_mov_b32_e32 v18, 0
	s_branch .LBB0_1679

; __device__ __forceinline__ unsigned xb_ld(unsigned* p)              { return __hip_atomic_load(p, __ATOMIC_RELAXED, __HIP_MEMORY_SCOPE_AGENT); }
; __device__ __forceinline__ unsigned xb_add(unsigned* p, unsigned v) { return __hip_atomic_fetch_add(p, v, __ATOMIC_RELAXED, __HIP_MEMORY_SCOPE_AGENT); }
; #define XB_SPIN(cond, bar) do { unsigned _sp = 0; while (cond) { __builtin_amdgcn_s_sleep(1); \
;     if ((++_sp & 255u) == 0u) { if (xb_ld(&(bar)[XB_TMO])) break; if (_sp > XB_SPIN_CAP) { atomicAdd(&(bar)[XB_TMO], 1u); break; } } } } while (0)
; __device__ __forceinline__ void xcd_barrier(const XcdBarrier& b) {
;     ...
;             else XB_SPIN(xb_ld(&bar[XB_TOPGEN]) == tg, bar);
;             __builtin_amdgcn_fence(__ATOMIC_ACQUIRE, "agent");
;             xb_add(&bar[XB_XGEN(b.x)], 1u);
;             asm volatile("s_waitcnt vmcnt(0)" ::: "memory");
;         } else {
;             XB_SPIN(xb_ld(&bar[XB_XGEN(b.x)]) == gen, bar);
;             __builtin_amdgcn_fence(__ATOMIC_ACQUIRE, "agent");
;             asm volatile("s_waitcnt vmcnt(0)" ::: "memory");
;         }
.Lgb2_done:
	s_waitcnt vmcnt(0)
.LBB0_1727:
	s_or_b64 exec, exec, s[4:5]
	s_mov_b64 s[4:5], 0
	s_waitcnt lgkmcnt(0)
	s_barrier

; __device__ __forceinline__ void xcd_barrier(const XcdBarrier& b) {
;     asm volatile("s_waitcnt vmcnt(0)" ::: "memory");
;     __syncthreads();
;     if (threadIdx.x == 0) {
;         unsigned* bar = b.bar;
;         __builtin_amdgcn_s_waitcnt(0);
;         unsigned nloc = b.st[0], nx = b.st[1];
;         if (nloc == 0u) { xcd_barrier_complete(bar, b.x, nloc, nx); b.st[0] = nloc; b.st[1] = nx; }
.LBB0_1951:
	s_cmp_lt_i32 s53, 6
	s_cbranch_scc1 .LBB0_2019
	s_cmpk_lt_u32 s53, 0x3e9
	s_mov_b64 s[4:5], -1
	s_cbranch_scc0 .LBB0_2006
	s_waitcnt vmcnt(0)
	s_waitcnt lgkmcnt(0)
	s_barrier
	s_and_saveexec_b64 s[4:5], s[86:87]
	s_cbranch_execz .LBB0_2005
	buffer_inv sc1
	v_mov_b32_e32 v2, 0x27ff0
	s_waitcnt lgkmcnt(0)
	ds_read_b32 v4, v2
	v_mov_b32_e32 v2, 0x27ff4
	ds_read_b32 v2, v2
	s_waitcnt lgkmcnt(1)
	v_cmp_ne_u32_e32 vcc, 0, v4
	s_cbranch_vccnz .LBB0_1969
	s_add_u32 s6, s66, 0x1000
	s_addc_u32 s7, s67, 0
	s_add_u32 s8, s66, 0x1100
	s_addc_u32 s9, s67, 0
	s_add_u32 s10, s66, 0x1200
	s_addc_u32 s11, s67, 0
	s_mul_i32 s3, s55, s84
	s_add_u32 s12, s66, 0x1300
	s_mul_i32 s3, s3, s54
	s_addc_u32 s13, s67, 0
	s_mov_b32 s20, 1
	v_mov_b32_e32 v18, 0
	s_branch .LBB0_1957

; __device__ __forceinline__ unsigned xb_ld(unsigned* p)              { return __hip_atomic_load(p, __ATOMIC_RELAXED, __HIP_MEMORY_SCOPE_AGENT); }
; __device__ __forceinline__ unsigned xb_add(unsigned* p, unsigned v) { return __hip_atomic_fetch_add(p, v, __ATOMIC_RELAXED, __HIP_MEMORY_SCOPE_AGENT); }
; #define XB_SPIN(cond, bar) do { unsigned _sp = 0; while (cond) { __builtin_amdgcn_s_sleep(1); \
;     if ((++_sp & 255u) == 0u) { if (xb_ld(&(bar)[XB_TMO])) break; if (_sp > XB_SPIN_CAP) { atomicAdd(&(bar)[XB_TMO], 1u); break; } } } } while (0)
; __device__ __forceinline__ void xcd_barrier(const XcdBarrier& b) {
;     ...
;             else XB_SPIN(xb_ld(&bar[XB_TOPGEN]) == tg, bar);
;             __builtin_amdgcn_fence(__ATOMIC_ACQUIRE, "agent");
;             xb_add(&bar[XB_XGEN(b.x)], 1u);
;             asm volatile("s_waitcnt vmcnt(0)" ::: "memory");
;         } else {
;             XB_SPIN(xb_ld(&bar[XB_XGEN(b.x)]) == gen, bar);
;             __builtin_amdgcn_fence(__ATOMIC_ACQUIRE, "agent");
;             asm volatile("s_waitcnt vmcnt(0)" ::: "memory");
;         }
.Lgb3_done:
	s_waitcnt vmcnt(0)
.LBB0_2005:
	s_or_b64 exec, exec, s[4:5]
	s_mov_b64 s[4:5], 0
	s_waitcnt lgkmcnt(0)
	s_barrier

; __device__ __forceinline__ void xcd_barrier(const XcdBarrier& b) {
;     asm volatile("s_waitcnt vmcnt(0)" ::: "memory");
;     __syncthreads();
;     if (threadIdx.x == 0) {
;         unsigned* bar = b.bar;
;         __builtin_amdgcn_s_waitcnt(0);
;         unsigned nloc = b.st[0], nx = b.st[1];
;         if (nloc == 0u) { xcd_barrier_complete(bar, b.x, nloc, nx); b.st[0] = nloc; b.st[1] = nx; }
.LBB0_2039:
	s_cmp_lt_i32 s53, 7
	s_cbranch_scc1 .LBB0_2107
	s_cmpk_lt_u32 s53, 0x3e9
	s_mov_b64 s[4:5], -1
	s_cbranch_scc0 .LBB0_2094
	s_waitcnt vmcnt(0)
	s_waitcnt lgkmcnt(0)
	s_barrier
	s_and_saveexec_b64 s[4:5], s[86:87]
	s_cbranch_execz .LBB0_2093
	buffer_inv sc1
	v_mov_b32_e32 v2, 0x27ff0
	s_waitcnt lgkmcnt(0)
	ds_read_b32 v4, v2
	v_mov_b32_e32 v2, 0x27ff4
	ds_read_b32 v2, v2
	s_waitcnt lgkmcnt(1)
	v_cmp_ne_u32_e32 vcc, 0, v4
	s_cbranch_vccnz .LBB0_2057
	s_add_u32 s6, s66, 0x1000
	s_addc_u32 s7, s67, 0
	s_add_u32 s8, s66, 0x1100
	s_addc_u32 s9, s67, 0
	s_add_u32 s10, s66, 0x1200
	s_addc_u32 s11, s67, 0
	s_mul_i32 s3, s55, s84
	s_add_u32 s12, s66, 0x1300
	s_mul_i32 s3, s3, s54
	s_addc_u32 s13, s67, 0
	s_mov_b32 s20, 1
	v_mov_b32_e32 v18, 0
	s_branch .LBB0_2045

; __device__ __forceinline__ unsigned xb_ld(unsigned* p)              { return __hip_atomic_load(p, __ATOMIC_RELAXED, __HIP_MEMORY_SCOPE_AGENT); }
; __device__ __forceinline__ unsigned xb_add(unsigned* p, unsigned v) { return __hip_atomic_fetch_add(p, v, __ATOMIC_RELAXED, __HIP_MEMORY_SCOPE_AGENT); }
; #define XB_SPIN(cond, bar) do { unsigned _sp = 0; while (cond) { __builtin_amdgcn_s_sleep(1); \
;     if ((++_sp & 255u) == 0u) { if (xb_ld(&(bar)[XB_TMO])) break; if (_sp > XB_SPIN_CAP) { atomicAdd(&(bar)[XB_TMO], 1u); break; } } } } while (0)
; __device__ __forceinline__ void xcd_barrier(const XcdBarrier& b) {
;     ...
;             else XB_SPIN(xb_ld(&bar[XB_TOPGEN]) == tg, bar);
;             __builtin_amdgcn_fence(__ATOMIC_ACQUIRE, "agent");
;             xb_add(&bar[XB_XGEN(b.x)], 1u);
;             asm volatile("s_waitcnt vmcnt(0)" ::: "memory");
;         } else {
;             XB_SPIN(xb_ld(&bar[XB_XGEN(b.x)]) == gen, bar);
;             __builtin_amdgcn_fence(__ATOMIC_ACQUIRE, "agent");
;             asm volatile("s_waitcnt vmcnt(0)" ::: "memory");
;         }
.Lgb4_done:
	s_waitcnt vmcnt(0)
.LBB0_2093:
	s_or_b64 exec, exec, s[4:5]
	s_mov_b64 s[4:5], 0
	s_waitcnt lgkmcnt(0)
	s_barrier

; __device__ __forceinline__ void xcd_barrier(const XcdBarrier& b) {
;     asm volatile("s_waitcnt vmcnt(0)" ::: "memory");
;     __syncthreads();
;     if (threadIdx.x == 0) {
;         unsigned* bar = b.bar;
;         __builtin_amdgcn_s_waitcnt(0);
;         unsigned nloc = b.st[0], nx = b.st[1];
;         if (nloc == 0u) { xcd_barrier_complete(bar, b.x, nloc, nx); b.st[0] = nloc; b.st[1] = nx; }
.LBB0_2181:
	s_cmp_lt_i32 s53, 8
	s_cbranch_scc1 .LBB0_2249
	s_cmpk_lt_u32 s53, 0x3e9
	s_mov_b64 s[4:5], -1
	s_cbranch_scc0 .LBB0_2236
	s_waitcnt vmcnt(0)
	s_waitcnt lgkmcnt(0)
	s_barrier
	s_and_saveexec_b64 s[4:5], s[86:87]
	s_cbranch_execz .LBB0_2235
	buffer_inv sc1
	v_mov_b32_e32 v2, 0x27ff0
	s_waitcnt lgkmcnt(0)
	ds_read_b32 v4, v2
	v_mov_b32_e32 v2, 0x27ff4
	ds_read_b32 v2, v2
	s_waitcnt lgkmcnt(1)
	v_cmp_ne_u32_e32 vcc, 0, v4
	s_cbranch_vccnz .LBB0_2199
	s_add_u32 s6, s66, 0x1000
	s_addc_u32 s7, s67, 0
	s_add_u32 s8, s66, 0x1100
	s_addc_u32 s9, s67, 0
	s_add_u32 s10, s66, 0x1200
	s_addc_u32 s11, s67, 0
	s_mul_i32 s3, s55, s84
	s_add_u32 s12, s66, 0x1300
	s_mul_i32 s3, s3, s54
	s_addc_u32 s13, s67, 0
	s_mov_b32 s20, 1
	v_mov_b32_e32 v18, 0
	s_branch .LBB0_2187

; __device__ __forceinline__ unsigned xb_ld(unsigned* p)              { return __hip_atomic_load(p, __ATOMIC_RELAXED, __HIP_MEMORY_SCOPE_AGENT); }
; __device__ __forceinline__ unsigned xb_add(unsigned* p, unsigned v) { return __hip_atomic_fetch_add(p, v, __ATOMIC_RELAXED, __HIP_MEMORY_SCOPE_AGENT); }
; #define XB_SPIN(cond, bar) do { unsigned _sp = 0; while (cond) { __builtin_amdgcn_s_sleep(1); \
;     if ((++_sp & 255u) == 0u) { if (xb_ld(&(bar)[XB_TMO])) break; if (_sp > XB_SPIN_CAP) { atomicAdd(&(bar)[XB_TMO], 1u); break; } } } } while (0)
; __device__ __forceinline__ void xcd_barrier(const XcdBarrier& b) {
;     ...
;             else XB_SPIN(xb_ld(&bar[XB_TOPGEN]) == tg, bar);
;             __builtin_amdgcn_fence(__ATOMIC_ACQUIRE, "agent");
;             xb_add(&bar[XB_XGEN(b.x)], 1u);
;             asm volatile("s_waitcnt vmcnt(0)" ::: "memory");
;         } else {
;             XB_SPIN(xb_ld(&bar[XB_XGEN(b.x)]) == gen, bar);
;             __builtin_amdgcn_fence(__ATOMIC_ACQUIRE, "agent");
;             asm volatile("s_waitcnt vmcnt(0)" ::: "memory");
;         }
.Lgb5_done:
	s_waitcnt vmcnt(0)
.LBB0_2235:
	s_or_b64 exec, exec, s[4:5]
	s_mov_b64 s[4:5], 0
	s_waitcnt lgkmcnt(0)
	s_barrier

; __device__ __forceinline__ void xcd_barrier(const XcdBarrier& b) {
;     asm volatile("s_waitcnt vmcnt(0)" ::: "memory");
;     __syncthreads();
;     if (threadIdx.x == 0) {
;         unsigned* bar = b.bar;
;         __builtin_amdgcn_s_waitcnt(0);
;         unsigned nloc = b.st[0], nx = b.st[1];
;         if (nloc == 0u) { xcd_barrier_complete(bar, b.x, nloc, nx); b.st[0] = nloc; b.st[1] = nx; }
.LBB0_2253:
	s_or_b64 exec, exec, s[6:7]
	s_cmp_lt_u32 s53, 9
	s_cbranch_scc1 .LBB0_2321
	s_cmpk_lt_u32 s53, 0x3e9
	s_mov_b64 s[4:5], -1
	s_cbranch_scc0 .LBB0_2308
	s_waitcnt vmcnt(0)
	s_waitcnt lgkmcnt(0)
	s_barrier
	s_and_saveexec_b64 s[4:5], s[86:87]
	s_cbranch_execz .LBB0_2307
	buffer_inv sc1
	v_mov_b32_e32 v2, 0x27ff0
	s_waitcnt lgkmcnt(0)
	ds_read_b32 v4, v2
	v_mov_b32_e32 v2, 0x27ff4
	ds_read_b32 v2, v2
	s_waitcnt lgkmcnt(1)
	v_cmp_ne_u32_e32 vcc, 0, v4
	s_cbranch_vccnz .LBB0_2271
	s_add_u32 s6, s66, 0x1000
	s_addc_u32 s7, s67, 0
	s_add_u32 s8, s66, 0x1100
	s_addc_u32 s9, s67, 0
	s_add_u32 s10, s66, 0x1200
	s_addc_u32 s11, s67, 0
	s_mul_i32 s3, s55, s84
	s_add_u32 s12, s66, 0x1300
	s_mul_i32 s3, s3, s54
	s_addc_u32 s13, s67, 0
	s_mov_b32 s20, 1
	v_mov_b32_e32 v18, 0
	s_branch .LBB0_2259

; __device__ __forceinline__ unsigned xb_ld(unsigned* p)              { return __hip_atomic_load(p, __ATOMIC_RELAXED, __HIP_MEMORY_SCOPE_AGENT); }
; __device__ __forceinline__ unsigned xb_add(unsigned* p, unsigned v) { return __hip_atomic_fetch_add(p, v, __ATOMIC_RELAXED, __HIP_MEMORY_SCOPE_AGENT); }
; #define XB_SPIN(cond, bar) do { unsigned _sp = 0; while (cond) { __builtin_amdgcn_s_sleep(1); \
;     if ((++_sp & 255u) == 0u) { if (xb_ld(&(bar)[XB_TMO])) break; if (_sp > XB_SPIN_CAP) { atomicAdd(&(bar)[XB_TMO], 1u); break; } } } } while (0)
; __device__ __forceinline__ void xcd_barrier(const XcdBarrier& b) {
;     ...
;             else XB_SPIN(xb_ld(&bar[XB_TOPGEN]) == tg, bar);
;             __builtin_amdgcn_fence(__ATOMIC_ACQUIRE, "agent");
;             xb_add(&bar[XB_XGEN(b.x)], 1u);
;             asm volatile("s_waitcnt vmcnt(0)" ::: "memory");
;         } else {
;             XB_SPIN(xb_ld(&bar[XB_XGEN(b.x)]) == gen, bar);
;             __builtin_amdgcn_fence(__ATOMIC_ACQUIRE, "agent");
;             asm volatile("s_waitcnt vmcnt(0)" ::: "memory");
;         }
.Lgb6_done:
	s_waitcnt vmcnt(0)
.LBB0_2307:
	s_or_b64 exec, exec, s[4:5]
	s_mov_b64 s[4:5], 0
	s_waitcnt lgkmcnt(0)
	s_barrier

; __device__ __forceinline__ void xcd_barrier(const XcdBarrier& b) {
;     asm volatile("s_waitcnt vmcnt(0)" ::: "memory");
;     __syncthreads();
;     if (threadIdx.x == 0) {
;         unsigned* bar = b.bar;
;         __builtin_amdgcn_s_waitcnt(0);
;         unsigned nloc = b.st[0], nx = b.st[1];
;         if (nloc == 0u) { xcd_barrier_complete(bar, b.x, nloc, nx); b.st[0] = nloc; b.st[1] = nx; }
.LBB0_2352:
	s_cmp_lt_i32 s53, 10
	s_cbranch_scc1 .LBB0_2420
	s_cmpk_lt_u32 s53, 0x3e9
	s_mov_b64 s[4:5], -1
	s_cbranch_scc0 .LBB0_2407
	s_waitcnt vmcnt(0)
	s_waitcnt lgkmcnt(0)
	s_barrier
	s_and_saveexec_b64 s[4:5], s[86:87]
	s_cbranch_execz .LBB0_2406
	buffer_inv sc1
	v_mov_b32_e32 v2, 0x27ff0
	s_waitcnt lgkmcnt(0)
	ds_read_b32 v4, v2
	v_mov_b32_e32 v2, 0x27ff4
	ds_read_b32 v2, v2
	s_waitcnt lgkmcnt(1)
	v_cmp_ne_u32_e32 vcc, 0, v4
	s_cbranch_vccnz .LBB0_2370
	s_add_u32 s6, s66, 0x1000
	s_addc_u32 s7, s67, 0
	s_add_u32 s8, s66, 0x1100
	s_addc_u32 s9, s67, 0
	s_add_u32 s10, s66, 0x1200
	s_addc_u32 s11, s67, 0
	s_mul_i32 s3, s55, s84
	s_add_u32 s12, s66, 0x1300
	s_mul_i32 s3, s3, s54
	s_addc_u32 s13, s67, 0
	s_mov_b32 s20, 1
	v_mov_b32_e32 v18, 0
	s_branch .LBB0_2358

; __device__ __forceinline__ unsigned xb_ld(unsigned* p)              { return __hip_atomic_load(p, __ATOMIC_RELAXED, __HIP_MEMORY_SCOPE_AGENT); }
; __device__ __forceinline__ unsigned xb_add(unsigned* p, unsigned v) { return __hip_atomic_fetch_add(p, v, __ATOMIC_RELAXED, __HIP_MEMORY_SCOPE_AGENT); }
; #define XB_SPIN(cond, bar) do { unsigned _sp = 0; while (cond) { __builtin_amdgcn_s_sleep(1); \
;     if ((++_sp & 255u) == 0u) { if (xb_ld(&(bar)[XB_TMO])) break; if (_sp > XB_SPIN_CAP) { atomicAdd(&(bar)[XB_TMO], 1u); break; } } } } while (0)
; __device__ __forceinline__ void xcd_barrier(const XcdBarrier& b) {
;     ...
;             else XB_SPIN(xb_ld(&bar[XB_TOPGEN]) == tg, bar);
;             __builtin_amdgcn_fence(__ATOMIC_ACQUIRE, "agent");
;             xb_add(&bar[XB_XGEN(b.x)], 1u);
;             asm volatile("s_waitcnt vmcnt(0)" ::: "memory");
;         } else {
;             XB_SPIN(xb_ld(&bar[XB_XGEN(b.x)]) == gen, bar);
;             __builtin_amdgcn_fence(__ATOMIC_ACQUIRE, "agent");
;             asm volatile("s_waitcnt vmcnt(0)" ::: "memory");
;         }
.Lgb7_done:
	s_waitcnt vmcnt(0)
.LBB0_2406:
	s_or_b64 exec, exec, s[4:5]
	s_mov_b64 s[4:5], 0
	s_waitcnt lgkmcnt(0)
	s_barrier

; __device__ __forceinline__ void xcd_barrier(const XcdBarrier& b) {
;     asm volatile("s_waitcnt vmcnt(0)" ::: "memory");
;     __syncthreads();
;     if (threadIdx.x == 0) {
;         unsigned* bar = b.bar;
;         __builtin_amdgcn_s_waitcnt(0);
;         unsigned nloc = b.st[0], nx = b.st[1];
;         if (nloc == 0u) { xcd_barrier_complete(bar, b.x, nloc, nx); b.st[0] = nloc; b.st[1] = nx; }
.LBB0_2494:
	s_cmp_lt_i32 s53, 11
	s_cbranch_scc1 .LBB0_2562
	s_cmpk_lt_u32 s53, 0x3e9
	s_mov_b64 s[4:5], -1
	s_cbranch_scc0 .LBB0_2549
	s_waitcnt vmcnt(0)
	s_waitcnt lgkmcnt(0)
	s_barrier
	s_and_saveexec_b64 s[4:5], s[86:87]
	s_cbranch_execz .LBB0_2548
	buffer_inv sc1
	v_mov_b32_e32 v2, 0x27ff0
	s_waitcnt lgkmcnt(0)
	ds_read_b32 v4, v2
	v_mov_b32_e32 v2, 0x27ff4
	ds_read_b32 v2, v2
	s_waitcnt lgkmcnt(1)
	v_cmp_ne_u32_e32 vcc, 0, v4
	s_cbranch_vccnz .LBB0_2512
	s_add_u32 s6, s66, 0x1000
	s_addc_u32 s7, s67, 0
	s_add_u32 s8, s66, 0x1100
	s_addc_u32 s9, s67, 0
	s_add_u32 s10, s66, 0x1200
	s_addc_u32 s11, s67, 0
	s_mul_i32 s3, s55, s84
	s_add_u32 s12, s66, 0x1300
	s_mul_i32 s3, s3, s54
	s_addc_u32 s13, s67, 0
	s_mov_b32 s20, 1
	v_mov_b32_e32 v18, 0
	s_branch .LBB0_2500

; __device__ __forceinline__ unsigned xb_ld(unsigned* p)              { return __hip_atomic_load(p, __ATOMIC_RELAXED, __HIP_MEMORY_SCOPE_AGENT); }
; __device__ __forceinline__ unsigned xb_add(unsigned* p, unsigned v) { return __hip_atomic_fetch_add(p, v, __ATOMIC_RELAXED, __HIP_MEMORY_SCOPE_AGENT); }
; #define XB_SPIN(cond, bar) do { unsigned _sp = 0; while (cond) { __builtin_amdgcn_s_sleep(1); \
;     if ((++_sp & 255u) == 0u) { if (xb_ld(&(bar)[XB_TMO])) break; if (_sp > XB_SPIN_CAP) { atomicAdd(&(bar)[XB_TMO], 1u); break; } } } } while (0)
; __device__ __forceinline__ void xcd_barrier(const XcdBarrier& b) {
;     ...
;             else XB_SPIN(xb_ld(&bar[XB_TOPGEN]) == tg, bar);
;             __builtin_amdgcn_fence(__ATOMIC_ACQUIRE, "agent");
;             xb_add(&bar[XB_XGEN(b.x)], 1u);
;             asm volatile("s_waitcnt vmcnt(0)" ::: "memory");
;         } else {
;             XB_SPIN(xb_ld(&bar[XB_XGEN(b.x)]) == gen, bar);
;             __builtin_amdgcn_fence(__ATOMIC_ACQUIRE, "agent");
;             asm volatile("s_waitcnt vmcnt(0)" ::: "memory");
;         }
.Lgb8_done:
	s_waitcnt vmcnt(0)
.LBB0_2548:
	s_or_b64 exec, exec, s[4:5]
	s_mov_b64 s[4:5], 0
	s_waitcnt lgkmcnt(0)
	s_barrier

; __device__ __forceinline__ void xcd_barrier(const XcdBarrier& b) {
;     asm volatile("s_waitcnt vmcnt(0)" ::: "memory");
;     __syncthreads();
;     if (threadIdx.x == 0) {
;         unsigned* bar = b.bar;
;         __builtin_amdgcn_s_waitcnt(0);
;         unsigned nloc = b.st[0], nx = b.st[1];
;         if (nloc == 0u) { xcd_barrier_complete(bar, b.x, nloc, nx); b.st[0] = nloc; b.st[1] = nx; }
.LBB0_2566:
	s_or_b64 exec, exec, s[6:7]
	s_cmp_lt_u32 s53, 12
	s_cbranch_scc1 .LBB0_2634
	s_cmpk_lt_u32 s53, 0x3e9
	s_mov_b64 s[4:5], -1
	s_cbranch_scc0 .LBB0_2621
	s_waitcnt vmcnt(0)
	s_waitcnt lgkmcnt(0)
	s_barrier
	s_and_saveexec_b64 s[4:5], s[86:87]
	s_cbranch_execz .LBB0_2620
	buffer_inv sc1
	v_mov_b32_e32 v2, 0x27ff0
	s_waitcnt lgkmcnt(0)
	ds_read_b32 v4, v2
	v_mov_b32_e32 v2, 0x27ff4
	ds_read_b32 v2, v2
	s_waitcnt lgkmcnt(1)
	v_cmp_ne_u32_e32 vcc, 0, v4
	s_cbranch_vccnz .LBB0_2584
	s_add_u32 s6, s66, 0x1000
	s_addc_u32 s7, s67, 0
	s_add_u32 s8, s66, 0x1100
	s_addc_u32 s9, s67, 0
	s_add_u32 s10, s66, 0x1200
	s_addc_u32 s11, s67, 0
	s_mul_i32 s3, s55, s84
	s_add_u32 s12, s66, 0x1300
	s_mul_i32 s3, s3, s54
	s_addc_u32 s13, s67, 0
	s_mov_b32 s20, 1
	v_mov_b32_e32 v18, 0
	s_branch .LBB0_2572

; __device__ __forceinline__ unsigned xb_ld(unsigned* p)              { return __hip_atomic_load(p, __ATOMIC_RELAXED, __HIP_MEMORY_SCOPE_AGENT); }
; __device__ __forceinline__ unsigned xb_add(unsigned* p, unsigned v) { return __hip_atomic_fetch_add(p, v, __ATOMIC_RELAXED, __HIP_MEMORY_SCOPE_AGENT); }
; #define XB_SPIN(cond, bar) do { unsigned _sp = 0; while (cond) { __builtin_amdgcn_s_sleep(1); \
;     if ((++_sp & 255u) == 0u) { if (xb_ld(&(bar)[XB_TMO])) break; if (_sp > XB_SPIN_CAP) { atomicAdd(&(bar)[XB_TMO], 1u); break; } } } } while (0)
; __device__ __forceinline__ void xcd_barrier(const XcdBarrier& b) {
;     ...
;             else XB_SPIN(xb_ld(&bar[XB_TOPGEN]) == tg, bar);
;             __builtin_amdgcn_fence(__ATOMIC_ACQUIRE, "agent");
;             xb_add(&bar[XB_XGEN(b.x)], 1u);
;             asm volatile("s_waitcnt vmcnt(0)" ::: "memory");
;         } else {
;             XB_SPIN(xb_ld(&bar[XB_XGEN(b.x)]) == gen, bar);
;             __builtin_amdgcn_fence(__ATOMIC_ACQUIRE, "agent");
;             asm volatile("s_waitcnt vmcnt(0)" ::: "memory");
;         }
.Lgb9_done:
	s_waitcnt vmcnt(0)
.LBB0_2620:
	s_or_b64 exec, exec, s[4:5]
	s_mov_b64 s[4:5], 0
	s_waitcnt lgkmcnt(0)
	s_barrier

; __device__ __forceinline__ void xcd_barrier(const XcdBarrier& b) {
;     asm volatile("s_waitcnt vmcnt(0)" ::: "memory");
;     __syncthreads();
;     if (threadIdx.x == 0) {
;         unsigned* bar = b.bar;
;         __builtin_amdgcn_s_waitcnt(0);
;         unsigned nloc = b.st[0], nx = b.st[1];
;         if (nloc == 0u) { xcd_barrier_complete(bar, b.x, nloc, nx); b.st[0] = nloc; b.st[1] = nx; }
.LBB0_2779:
	s_cmp_lt_i32 s53, 13
	s_cbranch_scc1 .LBB0_2847
	s_cmpk_lt_u32 s53, 0x3e9
	s_mov_b64 s[4:5], -1
	s_cbranch_scc0 .LBB0_2834
	s_waitcnt vmcnt(0)
	s_barrier
	s_and_saveexec_b64 s[4:5], s[86:87]
	s_cbranch_execz .LBB0_2833
	buffer_inv sc1
	v_mov_b32_e32 v2, 0x27ff0
	s_waitcnt lgkmcnt(0)
	ds_read_b32 v4, v2
	v_mov_b32_e32 v2, 0x27ff4
	ds_read_b32 v2, v2
	s_waitcnt lgkmcnt(1)
	v_cmp_ne_u32_e32 vcc, 0, v4
	s_cbranch_vccnz .LBB0_2797
	s_add_u32 s6, s66, 0x1000
	s_addc_u32 s7, s67, 0
	s_add_u32 s8, s66, 0x1100
	s_addc_u32 s9, s67, 0
	s_add_u32 s10, s66, 0x1200
	s_addc_u32 s11, s67, 0
	s_mul_i32 s3, s55, s84
	s_add_u32 s12, s66, 0x1300
	s_mul_i32 s3, s3, s54
	s_addc_u32 s13, s67, 0
	s_mov_b32 s20, 1
	v_mov_b32_e32 v18, 0
	s_branch .LBB0_2785

; __device__ __forceinline__ unsigned xb_ld(unsigned* p)              { return __hip_atomic_load(p, __ATOMIC_RELAXED, __HIP_MEMORY_SCOPE_AGENT); }
; __device__ __forceinline__ unsigned xb_add(unsigned* p, unsigned v) { return __hip_atomic_fetch_add(p, v, __ATOMIC_RELAXED, __HIP_MEMORY_SCOPE_AGENT); }
; #define XB_SPIN(cond, bar) do { unsigned _sp = 0; while (cond) { __builtin_amdgcn_s_sleep(1); \
;     if ((++_sp & 255u) == 0u) { if (xb_ld(&(bar)[XB_TMO])) break; if (_sp > XB_SPIN_CAP) { atomicAdd(&(bar)[XB_TMO], 1u); break; } } } } while (0)
; __device__ __forceinline__ void xcd_barrier(const XcdBarrier& b) {
;     ...
;             else XB_SPIN(xb_ld(&bar[XB_TOPGEN]) == tg, bar);
;             __builtin_amdgcn_fence(__ATOMIC_ACQUIRE, "agent");
;             xb_add(&bar[XB_XGEN(b.x)], 1u);
;             asm volatile("s_waitcnt vmcnt(0)" ::: "memory");
;         } else {
;             XB_SPIN(xb_ld(&bar[XB_XGEN(b.x)]) == gen, bar);
;             __builtin_amdgcn_fence(__ATOMIC_ACQUIRE, "agent");
;             asm volatile("s_waitcnt vmcnt(0)" ::: "memory");
;         }
.Lgb10_done:
	s_waitcnt vmcnt(0)
.LBB0_2833:
	s_or_b64 exec, exec, s[4:5]
	s_mov_b64 s[4:5], 0
	s_waitcnt lgkmcnt(0)
	s_barrier

; __device__ __forceinline__ void xcd_barrier(const XcdBarrier& b) {
;     asm volatile("s_waitcnt vmcnt(0)" ::: "memory");
;     __syncthreads();
;     if (threadIdx.x == 0) {
;         unsigned* bar = b.bar;
;         __builtin_amdgcn_s_waitcnt(0);
;         unsigned nloc = b.st[0], nx = b.st[1];
;         if (nloc == 0u) { xcd_barrier_complete(bar, b.x, nloc, nx); b.st[0] = nloc; b.st[1] = nx; }
.LBB0_2961:
	s_cmp_lt_i32 s53, 14
	s_cbranch_scc1 .LBB0_3029
	s_cmpk_lt_u32 s53, 0x3e9
	s_mov_b64 s[4:5], -1
	s_cbranch_scc0 .LBB0_3016
	s_waitcnt vmcnt(0)
	s_waitcnt lgkmcnt(0)
	s_barrier
	s_and_saveexec_b64 s[4:5], s[86:87]
	s_cbranch_execz .LBB0_3015
	buffer_inv sc1
	v_mov_b32_e32 v2, 0x27ff0
	s_waitcnt lgkmcnt(0)
	ds_read_b32 v4, v2
	v_mov_b32_e32 v2, 0x27ff4
	ds_read_b32 v2, v2
	s_waitcnt lgkmcnt(1)
	v_cmp_ne_u32_e32 vcc, 0, v4
	s_cbranch_vccnz .LBB0_2979
	s_add_u32 s6, s66, 0x1000
	s_addc_u32 s7, s67, 0
	s_add_u32 s8, s66, 0x1100
	s_addc_u32 s9, s67, 0
	s_add_u32 s10, s66, 0x1200
	s_addc_u32 s11, s67, 0
	s_mul_i32 s3, s55, s84
	s_add_u32 s12, s66, 0x1300
	s_mul_i32 s3, s3, s54
	s_addc_u32 s13, s67, 0
	s_mov_b32 s20, 1
	v_mov_b32_e32 v18, 0
	s_branch .LBB0_2967

; __device__ __forceinline__ unsigned xb_ld(unsigned* p)              { return __hip_atomic_load(p, __ATOMIC_RELAXED, __HIP_MEMORY_SCOPE_AGENT); }
; __device__ __forceinline__ unsigned xb_add(unsigned* p, unsigned v) { return __hip_atomic_fetch_add(p, v, __ATOMIC_RELAXED, __HIP_MEMORY_SCOPE_AGENT); }
; #define XB_SPIN(cond, bar) do { unsigned _sp = 0; while (cond) { __builtin_amdgcn_s_sleep(1); \
;     if ((++_sp & 255u) == 0u) { if (xb_ld(&(bar)[XB_TMO])) break; if (_sp > XB_SPIN_CAP) { atomicAdd(&(bar)[XB_TMO], 1u); break; } } } } while (0)
; __device__ __forceinline__ void xcd_barrier(const XcdBarrier& b) {
;     ...
;             else XB_SPIN(xb_ld(&bar[XB_TOPGEN]) == tg, bar);
;             __builtin_amdgcn_fence(__ATOMIC_ACQUIRE, "agent");
;             xb_add(&bar[XB_XGEN(b.x)], 1u);
;             asm volatile("s_waitcnt vmcnt(0)" ::: "memory");
;         } else {
;             XB_SPIN(xb_ld(&bar[XB_XGEN(b.x)]) == gen, bar);
;             __builtin_amdgcn_fence(__ATOMIC_ACQUIRE, "agent");
;             asm volatile("s_waitcnt vmcnt(0)" ::: "memory");
;         }
.Lgb11_done:
	s_waitcnt vmcnt(0)
.LBB0_3015:
	s_or_b64 exec, exec, s[4:5]
	s_mov_b64 s[4:5], 0
	s_waitcnt lgkmcnt(0)
	s_barrier

; __device__ __forceinline__ void xcd_barrier(const XcdBarrier& b) {
;     asm volatile("s_waitcnt vmcnt(0)" ::: "memory");
;     __syncthreads();
;     if (threadIdx.x == 0) {
;         unsigned* bar = b.bar;
;         __builtin_amdgcn_s_waitcnt(0);
;         unsigned nloc = b.st[0], nx = b.st[1];
;         if (nloc == 0u) { xcd_barrier_complete(bar, b.x, nloc, nx); b.st[0] = nloc; b.st[1] = nx; }
.LBB0_3033:
	s_cmp_lt_u32 s53, 15
	s_cbranch_scc1 .LBB0_3101
	s_cmpk_lt_u32 s53, 0x3e9
	s_mov_b64 s[4:5], -1
	s_cbranch_scc0 .LBB0_3088
	s_waitcnt vmcnt(0)
	s_waitcnt lgkmcnt(0)
	s_barrier
	s_and_saveexec_b64 s[4:5], s[86:87]
	s_cbranch_execz .LBB0_3087
	buffer_inv sc1
	v_mov_b32_e32 v2, 0x27ff0
	s_waitcnt lgkmcnt(0)
	ds_read_b32 v4, v2
	v_mov_b32_e32 v2, 0x27ff4
	ds_read_b32 v2, v2
	s_waitcnt lgkmcnt(1)
	v_cmp_ne_u32_e32 vcc, 0, v4
	s_cbranch_vccnz .LBB0_3051
	s_add_u32 s6, s66, 0x1000
	s_addc_u32 s7, s67, 0
	s_add_u32 s8, s66, 0x1100
	s_addc_u32 s9, s67, 0
	s_add_u32 s10, s66, 0x1200
	s_addc_u32 s11, s67, 0
	s_mul_i32 s3, s55, s84
	s_add_u32 s12, s66, 0x1300
	s_mul_i32 s3, s3, s54
	s_addc_u32 s13, s67, 0
	s_mov_b32 s20, 1
	v_mov_b32_e32 v18, 0
	s_branch .LBB0_3039

; __device__ __forceinline__ unsigned xb_ld(unsigned* p)              { return __hip_atomic_load(p, __ATOMIC_RELAXED, __HIP_MEMORY_SCOPE_AGENT); }
; __device__ __forceinline__ unsigned xb_add(unsigned* p, unsigned v) { return __hip_atomic_fetch_add(p, v, __ATOMIC_RELAXED, __HIP_MEMORY_SCOPE_AGENT); }
; #define XB_SPIN(cond, bar) do { unsigned _sp = 0; while (cond) { __builtin_amdgcn_s_sleep(1); \
;     if ((++_sp & 255u) == 0u) { if (xb_ld(&(bar)[XB_TMO])) break; if (_sp > XB_SPIN_CAP) { atomicAdd(&(bar)[XB_TMO], 1u); break; } } } } while (0)
; __device__ __forceinline__ void xcd_barrier(const XcdBarrier& b) {
;     ...
;             else XB_SPIN(xb_ld(&bar[XB_TOPGEN]) == tg, bar);
;             __builtin_amdgcn_fence(__ATOMIC_ACQUIRE, "agent");
;             xb_add(&bar[XB_XGEN(b.x)], 1u);
;             asm volatile("s_waitcnt vmcnt(0)" ::: "memory");
;         } else {
;             XB_SPIN(xb_ld(&bar[XB_XGEN(b.x)]) == gen, bar);
;             __builtin_amdgcn_fence(__ATOMIC_ACQUIRE, "agent");
;             asm volatile("s_waitcnt vmcnt(0)" ::: "memory");
;         }
.Lgb12_done:
	s_waitcnt vmcnt(0)
.LBB0_3087:
	s_or_b64 exec, exec, s[4:5]
	s_mov_b64 s[4:5], 0
	s_waitcnt lgkmcnt(0)
	s_barrier

; __device__ __forceinline__ void xcd_barrier(const XcdBarrier& b) {
;     asm volatile("s_waitcnt vmcnt(0)" ::: "memory");
;     __syncthreads();
;     if (threadIdx.x == 0) {
;         unsigned* bar = b.bar;
;         __builtin_amdgcn_s_waitcnt(0);
;         unsigned nloc = b.st[0], nx = b.st[1];
;         if (nloc == 0u) { xcd_barrier_complete(bar, b.x, nloc, nx); b.st[0] = nloc; b.st[1] = nx; }
.LBB0_3271:
	s_cmp_lt_i32 s53, 16
	s_cbranch_scc1 .LBB0_3339
	s_cmpk_lt_u32 s53, 0x3e9
	s_mov_b64 s[4:5], -1
	s_cbranch_scc0 .LBB0_3326
	s_waitcnt vmcnt(0)
	s_waitcnt lgkmcnt(0)
	s_barrier
	s_and_saveexec_b64 s[4:5], s[86:87]
	s_cbranch_execz .LBB0_3325
	buffer_inv sc1
	v_mov_b32_e32 v2, 0x27ff0
	s_waitcnt lgkmcnt(0)
	ds_read_b32 v4, v2
	v_mov_b32_e32 v2, 0x27ff4
	ds_read_b32 v2, v2
	s_waitcnt lgkmcnt(1)
	v_cmp_ne_u32_e32 vcc, 0, v4
	s_cbranch_vccnz .LBB0_3289
	s_add_u32 s6, s66, 0x1000
	s_addc_u32 s7, s67, 0
	s_add_u32 s8, s66, 0x1100
	s_addc_u32 s9, s67, 0
	s_add_u32 s10, s66, 0x1200
	s_addc_u32 s11, s67, 0
	s_mul_i32 s3, s55, s84
	s_add_u32 s12, s66, 0x1300
	s_mul_i32 s3, s3, s54
	s_addc_u32 s13, s67, 0
	s_mov_b32 s20, 1
	v_mov_b32_e32 v18, 0
	s_branch .LBB0_3277

; __device__ __forceinline__ unsigned xb_ld(unsigned* p)              { return __hip_atomic_load(p, __ATOMIC_RELAXED, __HIP_MEMORY_SCOPE_AGENT); }
; __device__ __forceinline__ unsigned xb_add(unsigned* p, unsigned v) { return __hip_atomic_fetch_add(p, v, __ATOMIC_RELAXED, __HIP_MEMORY_SCOPE_AGENT); }
; #define XB_SPIN(cond, bar) do { unsigned _sp = 0; while (cond) { __builtin_amdgcn_s_sleep(1); \
;     if ((++_sp & 255u) == 0u) { if (xb_ld(&(bar)[XB_TMO])) break; if (_sp > XB_SPIN_CAP) { atomicAdd(&(bar)[XB_TMO], 1u); break; } } } } while (0)
; __device__ __forceinline__ void xcd_barrier(const XcdBarrier& b) {
;     ...
;             else XB_SPIN(xb_ld(&bar[XB_TOPGEN]) == tg, bar);
;             __builtin_amdgcn_fence(__ATOMIC_ACQUIRE, "agent");
;             xb_add(&bar[XB_XGEN(b.x)], 1u);
;             asm volatile("s_waitcnt vmcnt(0)" ::: "memory");
;         } else {
;             XB_SPIN(xb_ld(&bar[XB_XGEN(b.x)]) == gen, bar);
;             __builtin_amdgcn_fence(__ATOMIC_ACQUIRE, "agent");
;             asm volatile("s_waitcnt vmcnt(0)" ::: "memory");
;         }
.Lgb13_done:
	s_waitcnt vmcnt(0)
.LBB0_3325:
	s_or_b64 exec, exec, s[4:5]
	s_mov_b64 s[4:5], 0
	s_waitcnt lgkmcnt(0)
	s_barrier

; __device__ __forceinline__ void xcd_barrier(const XcdBarrier& b) {
;     asm volatile("s_waitcnt vmcnt(0)" ::: "memory");
;     __syncthreads();
;     if (threadIdx.x == 0) {
;         unsigned* bar = b.bar;
;         __builtin_amdgcn_s_waitcnt(0);
;         unsigned nloc = b.st[0], nx = b.st[1];
;         if (nloc == 0u) { xcd_barrier_complete(bar, b.x, nloc, nx); b.st[0] = nloc; b.st[1] = nx; }
.LBB0_3343:
	s_or_b64 exec, exec, s[6:7]
	s_cmp_lt_u32 s53, 17
	s_cbranch_scc1 .LBB0_3411
	s_cmpk_lt_u32 s53, 0x3e9
	s_mov_b64 s[4:5], -1
	s_cbranch_scc0 .LBB0_3398
	s_waitcnt vmcnt(0)
	s_waitcnt lgkmcnt(0)
	s_barrier
	s_and_saveexec_b64 s[4:5], s[86:87]
	s_cbranch_execz .LBB0_3397
	buffer_inv sc1
	v_mov_b32_e32 v2, 0x27ff0
	s_waitcnt lgkmcnt(0)
	ds_read_b32 v4, v2
	v_mov_b32_e32 v2, 0x27ff4
	ds_read_b32 v2, v2
	s_waitcnt lgkmcnt(1)
	v_cmp_ne_u32_e32 vcc, 0, v4
	s_cbranch_vccnz .LBB0_3361
	s_add_u32 s6, s66, 0x1000
	s_addc_u32 s7, s67, 0
	s_add_u32 s8, s66, 0x1100
	s_addc_u32 s9, s67, 0
	s_add_u32 s10, s66, 0x1200
	s_addc_u32 s11, s67, 0
	s_mul_i32 s3, s55, s84
	s_add_u32 s12, s66, 0x1300
	s_mul_i32 s3, s3, s54
	s_addc_u32 s13, s67, 0
	s_mov_b32 s20, 1
	v_mov_b32_e32 v18, 0
	s_branch .LBB0_3349

; __device__ __forceinline__ unsigned xb_ld(unsigned* p)              { return __hip_atomic_load(p, __ATOMIC_RELAXED, __HIP_MEMORY_SCOPE_AGENT); }
; __device__ __forceinline__ unsigned xb_add(unsigned* p, unsigned v) { return __hip_atomic_fetch_add(p, v, __ATOMIC_RELAXED, __HIP_MEMORY_SCOPE_AGENT); }
; #define XB_SPIN(cond, bar) do { unsigned _sp = 0; while (cond) { __builtin_amdgcn_s_sleep(1); \
;     if ((++_sp & 255u) == 0u) { if (xb_ld(&(bar)[XB_TMO])) break; if (_sp > XB_SPIN_CAP) { atomicAdd(&(bar)[XB_TMO], 1u); break; } } } } while (0)
; __device__ __forceinline__ void xcd_barrier(const XcdBarrier& b) {
;     ...
;             else XB_SPIN(xb_ld(&bar[XB_TOPGEN]) == tg, bar);
;             __builtin_amdgcn_fence(__ATOMIC_ACQUIRE, "agent");
;             xb_add(&bar[XB_XGEN(b.x)], 1u);
;             asm volatile("s_waitcnt vmcnt(0)" ::: "memory");
;         } else {
;             XB_SPIN(xb_ld(&bar[XB_XGEN(b.x)]) == gen, bar);
;             __builtin_amdgcn_fence(__ATOMIC_ACQUIRE, "agent");
;             asm volatile("s_waitcnt vmcnt(0)" ::: "memory");
;         }
.Lgb14_done:
	s_waitcnt vmcnt(0)
.LBB0_3397:
	s_or_b64 exec, exec, s[4:5]
	s_mov_b64 s[4:5], 0
	s_waitcnt lgkmcnt(0)
	s_barrier

; __device__ __forceinline__ void xcd_barrier(const XcdBarrier& b) {
;     asm volatile("s_waitcnt vmcnt(0)" ::: "memory");
;     __syncthreads();
;     if (threadIdx.x == 0) {
;         unsigned* bar = b.bar;
;         __builtin_amdgcn_s_waitcnt(0);
;         unsigned nloc = b.st[0], nx = b.st[1];
;         if (nloc == 0u) { xcd_barrier_complete(bar, b.x, nloc, nx); b.st[0] = nloc; b.st[1] = nx; }
.LBB0_3439:
	s_cmp_lt_i32 s53, 18
	s_cbranch_scc1 .LBB0_3507
	s_cmpk_lt_u32 s53, 0x3e9
	s_mov_b64 s[4:5], -1
	s_cbranch_scc0 .LBB0_3494
	s_waitcnt vmcnt(0)
	s_waitcnt lgkmcnt(0)
	s_barrier
	s_and_saveexec_b64 s[4:5], s[86:87]
	s_cbranch_execz .LBB0_3493
	buffer_inv sc1
	v_mov_b32_e32 v2, 0x27ff0
	s_waitcnt lgkmcnt(0)
	ds_read_b32 v4, v2
	v_mov_b32_e32 v2, 0x27ff4
	ds_read_b32 v2, v2
	s_waitcnt lgkmcnt(1)
	v_cmp_ne_u32_e32 vcc, 0, v4
	s_cbranch_vccnz .LBB0_3457
	s_add_u32 s6, s66, 0x1000
	s_addc_u32 s7, s67, 0
	s_add_u32 s8, s66, 0x1100
	s_addc_u32 s9, s67, 0
	s_add_u32 s10, s66, 0x1200
	s_addc_u32 s11, s67, 0
	s_mul_i32 s3, s55, s84
	s_add_u32 s12, s66, 0x1300
	s_mul_i32 s3, s3, s54
	s_addc_u32 s13, s67, 0
	s_mov_b32 s20, 1
	v_mov_b32_e32 v18, 0
	s_branch .LBB0_3445

; __device__ __forceinline__ unsigned xb_ld(unsigned* p)              { return __hip_atomic_load(p, __ATOMIC_RELAXED, __HIP_MEMORY_SCOPE_AGENT); }
; __device__ __forceinline__ unsigned xb_add(unsigned* p, unsigned v) { return __hip_atomic_fetch_add(p, v, __ATOMIC_RELAXED, __HIP_MEMORY_SCOPE_AGENT); }
; #define XB_SPIN(cond, bar) do { unsigned _sp = 0; while (cond) { __builtin_amdgcn_s_sleep(1); \
;     if ((++_sp & 255u) == 0u) { if (xb_ld(&(bar)[XB_TMO])) break; if (_sp > XB_SPIN_CAP) { atomicAdd(&(bar)[XB_TMO], 1u); break; } } } } while (0)
; __device__ __forceinline__ void xcd_barrier(const XcdBarrier& b) {
;     ...
;             else XB_SPIN(xb_ld(&bar[XB_TOPGEN]) == tg, bar);
;             __builtin_amdgcn_fence(__ATOMIC_ACQUIRE, "agent");
;             xb_add(&bar[XB_XGEN(b.x)], 1u);
;             asm volatile("s_waitcnt vmcnt(0)" ::: "memory");
;         } else {
;             XB_SPIN(xb_ld(&bar[XB_XGEN(b.x)]) == gen, bar);
;             __builtin_amdgcn_fence(__ATOMIC_ACQUIRE, "agent");
;             asm volatile("s_waitcnt vmcnt(0)" ::: "memory");
;         }
.Lgb15_done:
	s_waitcnt vmcnt(0)
.LBB0_3493:
	s_or_b64 exec, exec, s[4:5]
	s_mov_b64 s[4:5], 0
	s_waitcnt lgkmcnt(0)
	s_barrier

; __device__ __forceinline__ void xcd_barrier(const XcdBarrier& b) {
;     asm volatile("s_waitcnt vmcnt(0)" ::: "memory");
;     __syncthreads();
;     if (threadIdx.x == 0) {
;         unsigned* bar = b.bar;
;         __builtin_amdgcn_s_waitcnt(0);
;         unsigned nloc = b.st[0], nx = b.st[1];
;         if (nloc == 0u) { xcd_barrier_complete(bar, b.x, nloc, nx); b.st[0] = nloc; b.st[1] = nx; }
.LBB0_3581:
	s_cmp_lt_i32 s53, 19
	s_cbranch_scc1 .LBB0_3649
	s_cmpk_lt_u32 s53, 0x3e9
	s_mov_b64 s[4:5], -1
	s_cbranch_scc0 .LBB0_3636
	s_waitcnt vmcnt(0)
	s_waitcnt lgkmcnt(0)
	s_barrier
	s_and_saveexec_b64 s[4:5], s[86:87]
	s_cbranch_execz .LBB0_3635
	buffer_inv sc1
	v_mov_b32_e32 v2, 0x27ff0
	s_waitcnt lgkmcnt(0)
	ds_read_b32 v4, v2
	v_mov_b32_e32 v2, 0x27ff4
	ds_read_b32 v2, v2
	s_waitcnt lgkmcnt(1)
	v_cmp_ne_u32_e32 vcc, 0, v4
	s_cbranch_vccnz .LBB0_3599
	s_add_u32 s6, s66, 0x1000
	s_addc_u32 s7, s67, 0
	s_add_u32 s8, s66, 0x1100
	s_addc_u32 s9, s67, 0
	s_add_u32 s10, s66, 0x1200
	s_addc_u32 s11, s67, 0
	s_mul_i32 s3, s55, s84
	s_add_u32 s12, s66, 0x1300
	s_mul_i32 s3, s3, s54
	s_addc_u32 s13, s67, 0
	s_mov_b32 s20, 1
	v_mov_b32_e32 v18, 0
	s_branch .LBB0_3587

; __device__ __forceinline__ unsigned xb_ld(unsigned* p)              { return __hip_atomic_load(p, __ATOMIC_RELAXED, __HIP_MEMORY_SCOPE_AGENT); }
; __device__ __forceinline__ unsigned xb_add(unsigned* p, unsigned v) { return __hip_atomic_fetch_add(p, v, __ATOMIC_RELAXED, __HIP_MEMORY_SCOPE_AGENT); }
; #define XB_SPIN(cond, bar) do { unsigned _sp = 0; while (cond) { __builtin_amdgcn_s_sleep(1); \
;     if ((++_sp & 255u) == 0u) { if (xb_ld(&(bar)[XB_TMO])) break; if (_sp > XB_SPIN_CAP) { atomicAdd(&(bar)[XB_TMO], 1u); break; } } } } while (0)
; __device__ __forceinline__ void xcd_barrier(const XcdBarrier& b) {
;     ...
;             else XB_SPIN(xb_ld(&bar[XB_TOPGEN]) == tg, bar);
;             __builtin_amdgcn_fence(__ATOMIC_ACQUIRE, "agent");
;             xb_add(&bar[XB_XGEN(b.x)], 1u);
;             asm volatile("s_waitcnt vmcnt(0)" ::: "memory");
;         } else {
;             XB_SPIN(xb_ld(&bar[XB_XGEN(b.x)]) == gen, bar);
;             __builtin_amdgcn_fence(__ATOMIC_ACQUIRE, "agent");
;             asm volatile("s_waitcnt vmcnt(0)" ::: "memory");
;         }
.Lgb16_done:
	s_waitcnt vmcnt(0)
.LBB0_3635:
	s_or_b64 exec, exec, s[4:5]
	s_mov_b64 s[4:5], 0
	s_waitcnt lgkmcnt(0)
	s_barrier
